# NSA prompt tiles: issue 4 K reads + 8 V^T LDS reads up front with counted lgkmcnt (on top of WINROWS removal)
# baseline (speedup 1.0000x reference)
; #define LAS __attribute__((address_space(3)))
; DI void tile_online(AState& st, const LAS bf16* Kt, int KP, const LAS bf16* Vt, int VP, const bf16x8 (&qf)[4], int kbase, int lo, int hi, bool flag, int r, int h) {
;     const bool any = flag && (kbase + 31 >= lo) && (kbase <= hi);
;     if (__ballot(any) == 0ull) return;
;     f32x16 s = qk_tile32(Kt, KP, qf, r, h);
;     const bool cut = flag && !((kbase >= lo) && (kbase + 31 <= hi));
;     float mx = -__builtin_inff();
;     if (__ballot(cut) != 0ull) {
;         const unsigned t0 = (unsigned)(kbase + 4 * h - lo), range = (unsigned)(hi - lo);
; #pragma unroll
;         for (int reg = 0; reg < 16; ++reg) { s[reg] = (t0 + (unsigned)((reg & 3) + 8 * (reg >> 2)) <= range) ? s[reg] : -__builtin_inff(); mx = fmaxf(mx, s[reg]); }
;     } else {
; #pragma unroll
;         for (int reg = 0; reg < 16; ++reg) mx = fmaxf(mx, s[reg]);
;     }
; DI void nsa_prompt_unit(Frame& F, int b, int kv, int c) {
;     ...
;             { const bool fl = (selmask >> j) & 1u;
;               tile_online(st, KT0, KTP, VT0, VTP, qf, 64 * j, 0, qpos, fl, r, h);
;               tile_online(st, KT0 + 32 * KTP, KTP, VT0 + 32 * VTP, VTP, qf, 64 * j + 32, 0, qpos, fl, r, h);
.LBB0_1645:
	v_lshrrev_b32_e32 v2, s0, v100
	v_and_b32_e32 v36, 1, v2
	s_add_i32 s2, s13, 0xffffff81
	v_cmp_eq_u32_e64 s[0:1], 1, v36
	v_cmp_le_i32_e32 vcc, s2, v104
	s_and_b64 s[2:3], vcc, s[0:1]
	v_cndmask_b32_e64 v36, 0, 1, s[2:3]
	v_cmp_ne_u32_e32 vcc, 0, v36
	s_cbranch_vccz .LBB0_1652
	ds_read_b128 v[36:39], v105
	ds_read_b128 v[40:43], v105 offset:32
	ds_read_b128 v[44:47], v105 offset:64
	ds_read_b128 v[48:51], v105 offset:96
	ds_read_b64_tr_b16 v[126:127], v112 offset:9216
	ds_read_b64_tr_b16 v[128:129], v112 offset:10368
	ds_read_b64_tr_b16 v[130:131], v112 offset:9280
	ds_read_b64_tr_b16 v[132:133], v112 offset:10432
	ds_read_b64_tr_b16 v[134:135], v112 offset:11520
	ds_read_b64_tr_b16 v[136:137], v112 offset:12672
	ds_read_b64_tr_b16 v[138:139], v112 offset:11584
	ds_read_b64_tr_b16 v[140:141], v112 offset:12736
	s_add_i32 s8, s13, 0xffffffa0
	v_cmp_gt_i32_e32 vcc, s8, v104
	s_and_b64 s[8:9], s[0:1], vcc
	s_waitcnt lgkmcnt(11)
	v_mfma_f32_32x32x16_bf16 v[52:67], v[36:39], v[68:71], 0
	s_waitcnt lgkmcnt(10)
	v_mfma_f32_32x32x16_bf16 v[52:67], v[40:43], v[72:75], v[52:67]
	s_waitcnt lgkmcnt(9)
	v_mfma_f32_32x32x16_bf16 v[52:67], v[44:47], v[76:79], v[52:67]
	s_waitcnt lgkmcnt(8)
	v_mfma_f32_32x32x16_bf16 v[52:67], v[48:51], v[80:83], v[52:67]
	v_cndmask_b32_e64 v36, 0, 1, s[8:9]
	v_cmp_ne_u32_e32 vcc, 0, v36
	s_cbranch_vccz .LBB0_1677
	v_add_u32_e32 v51, s13, v111
	v_add_u32_e32 v37, 0xffffff81, v51
	v_cmp_le_u32_e32 vcc, v37, v104
	v_add_u32_e32 v38, 0xffffff83, v51
	v_add_u32_e32 v39, 0xffffff84, v51
	s_nop 3
	v_cndmask_b32_e32 v36, v231, v52, vcc
	v_cmp_lt_u32_e32 vcc, v37, v104
	v_add_u32_e32 v41, 0xffffff8a, v51
	v_add_u32_e32 v43, 0xffffff8c, v51
	v_cndmask_b32_e32 v37, v231, v53, vcc
	v_cmp_le_u32_e32 vcc, v38, v104
	v_max3_f32 v40, v36, s40, v37
	v_add_u32_e32 v45, 0xffffff92, v51
	v_cndmask_b32_e32 v38, v231, v54, vcc
	v_cmp_le_u32_e32 vcc, v39, v104
	v_add_u32_e32 v47, 0xffffff94, v51
	v_add_u32_e32 v49, 0xffffff9a, v51
	v_cndmask_b32_e32 v39, v231, v55, vcc
	v_max3_f32 v42, v40, v38, v39
	v_add_u32_e32 v40, 0xffffff89, v51
	v_cmp_le_u32_e32 vcc, v40, v104
	s_nop 1
	v_cndmask_b32_e32 v40, v231, v56, vcc
	v_cmp_le_u32_e32 vcc, v41, v104
	s_nop 1
	v_cndmask_b32_e32 v41, v231, v57, vcc
	v_max3_f32 v44, v42, v40, v41
	v_add_u32_e32 v42, 0xffffff8b, v51
	v_cmp_le_u32_e32 vcc, v42, v104
	s_nop 1
	v_cndmask_b32_e32 v42, v231, v58, vcc
	v_cmp_le_u32_e32 vcc, v43, v104
	s_nop 1
	v_cndmask_b32_e32 v43, v231, v59, vcc
	v_max3_f32 v46, v44, v42, v43
	v_add_u32_e32 v44, 0xffffff91, v51
	v_cmp_le_u32_e32 vcc, v44, v104
	s_nop 1
	v_cndmask_b32_e32 v44, v231, v60, vcc
	v_cmp_le_u32_e32 vcc, v45, v104
	s_nop 1
	v_cndmask_b32_e32 v45, v231, v61, vcc
	v_max3_f32 v48, v46, v44, v45
	v_add_u32_e32 v46, 0xffffff93, v51
	v_cmp_le_u32_e32 vcc, v46, v104
	s_nop 1
	v_cndmask_b32_e32 v46, v231, v62, vcc
	v_cmp_le_u32_e32 vcc, v47, v104
	s_nop 1
	v_cndmask_b32_e32 v47, v231, v63, vcc
	v_max3_f32 v50, v48, v46, v47
	v_add_u32_e32 v48, 0xffffff99, v51
	v_cmp_le_u32_e32 vcc, v48, v104
	s_nop 1
	v_cndmask_b32_e32 v48, v231, v64, vcc
	v_cmp_le_u32_e32 vcc, v49, v104
	s_nop 1
	v_cndmask_b32_e32 v49, v231, v65, vcc
	v_max3_f32 v116, v50, v48, v49
	v_add_u32_e32 v50, 0xffffff9b, v51
	v_cmp_le_u32_e32 vcc, v50, v104
	v_add_u32_e32 v51, 0xffffff9c, v51
	s_nop 0
	v_cndmask_b32_e32 v50, v231, v66, vcc
	v_cmp_le_u32_e32 vcc, v51, v104
	s_nop 1
	v_cndmask_b32_e32 v51, v231, v67, vcc
	v_max3_f32 v116, v116, v50, v51
	s_cbranch_execnz .LBB0_1649

; #define LAS __attribute__((address_space(3)))
; DI float fexp2(float x) { return __builtin_amdgcn_exp2f(x); }
; DI float xhalf_sum(float v) { return v + __shfl_xor(v, 32); }
; DI void tile_online(AState& st, const LAS bf16* Kt, int KP, const LAS bf16* Vt, int VP, const bf16x8 (&qf)[4], int kbase, int lo, int hi, bool flag, int r, int h) {
;     const bool any = flag && (kbase + 31 >= lo) && (kbase <= hi);
;     if (__ballot(any) == 0ull) return;
;     f32x16 s = qk_tile32(Kt, KP, qf, r, h);
;     const bool cut = flag && !((kbase >= lo) && (kbase + 31 <= hi));
;     float mx = -__builtin_inff();
;     if (__ballot(cut) != 0ull) {
;         const unsigned t0 = (unsigned)(kbase + 4 * h - lo), range = (unsigned)(hi - lo);
; #pragma unroll
;         for (int reg = 0; reg < 16; ++reg) { s[reg] = (t0 + (unsigned)((reg & 3) + 8 * (reg >> 2)) <= range) ? s[reg] : -__builtin_inff(); mx = fmaxf(mx, s[reg]); }
;     } else {
; #pragma unroll
;         for (int reg = 0; reg < 16; ++reg) mx = fmaxf(mx, s[reg]);
;     }
;     ...
;     const float mn = st.m;
;     const float bias = any ? -mn * LOG2E : -__builtin_inff();
;     f32x2 sum2 = {0.f, 0.f}; const f32x2 b2 = {bias, bias}, l2 = {LOG2E, LOG2E};
; #pragma unroll
;     for (int reg = 0; reg < 16; reg += 2) { f32x2 t = {s[reg], s[reg + 1]}; t = __builtin_elementwise_fma(t, l2, b2);
;         t[0] = fexp2(t[0]); t[1] = fexp2(t[1]); s[reg] = t[0]; s[reg + 1] = t[1]; sum2 = sum2 + t; }
;     st.l += xhalf_sum(sum2[0] + sum2[1]);
;     pv_tile32(st.o0, st.o1, Vt, VP, s, r + 32 * h);
; }
.LBB0_1651:
	v_mul_f32_e32 v52, 0xbfb8aa3b, v115
	v_cndmask_b32_e64 v52, v231, v52, s[2:3]
	v_pk_fma_f32 v[36:37], v[36:37], s[38:39], v[52:53] op_sel_hi:[1,0,0]
	v_pk_fma_f32 v[38:39], v[38:39], s[38:39], v[52:53] op_sel_hi:[1,0,0]
	v_exp_f32_e32 v36, v36
	v_exp_f32_e32 v37, v37
	v_exp_f32_e32 v38, v38
	v_exp_f32_e32 v39, v39
	v_pk_fma_f32 v[40:41], v[40:41], s[38:39], v[52:53] op_sel_hi:[1,0,0]
	v_pk_fma_f32 v[42:43], v[42:43], s[38:39], v[52:53] op_sel_hi:[1,0,0]
	v_exp_f32_e32 v40, v40
	v_exp_f32_e32 v41, v41
	v_exp_f32_e32 v42, v42
	v_exp_f32_e32 v43, v43
	v_pk_add_f32 v[54:55], v[36:37], 0 op_sel_hi:[1,0]
	v_cvt_pk_bf16_f32 v36, v36, v37
	v_pk_add_f32 v[54:55], v[38:39], v[54:55]
	v_cvt_pk_bf16_f32 v37, v38, v39
	v_pk_add_f32 v[54:55], v[40:41], v[54:55]
	v_cvt_pk_bf16_f32 v38, v40, v41
	v_pk_add_f32 v[54:55], v[42:43], v[54:55]
	v_cvt_pk_bf16_f32 v39, v42, v43
	s_waitcnt lgkmcnt(0)
	v_mfma_f32_32x32x16_bf16 v[20:35], v[126:129], v[36:39], v[20:35]
	v_fma_f32 v44, v44, s38, v52
	v_fma_f32 v45, v45, s38, v52
	v_fma_f32 v46, v46, s38, v52
	v_fma_f32 v47, v47, s38, v52
	v_pk_fma_f32 v[48:49], v[48:49], s[38:39], v[52:53] op_sel_hi:[1,0,0]
	v_pk_fma_f32 v[50:51], v[50:51], s[38:39], v[52:53] op_sel_hi:[1,0,0]
	v_exp_f32_e32 v44, v44
	v_exp_f32_e32 v45, v45
	v_exp_f32_e32 v46, v46
	v_exp_f32_e32 v47, v47
	v_exp_f32_e32 v48, v48
	v_exp_f32_e32 v49, v49
	v_exp_f32_e32 v50, v50
	v_exp_f32_e32 v51, v51
	s_waitcnt lgkmcnt(0)
	v_mfma_f32_32x32x16_bf16 v[4:19], v[130:133], v[36:39], v[4:19]
	v_cvt_pk_bf16_f32 v36, v44, v45
	v_cvt_pk_bf16_f32 v37, v46, v47
	v_cvt_pk_bf16_f32 v38, v48, v49
	v_cvt_pk_bf16_f32 v39, v50, v51
	v_pk_add_f32 v[54:55], v[44:45], v[54:55]
	s_waitcnt lgkmcnt(0)
	v_mfma_f32_32x32x16_bf16 v[20:35], v[134:137], v[36:39], v[20:35]
	v_add_f32_e64 v54, v46, v54
	v_add_f32_e64 v55, v47, v55
	v_add_f32_e64 v54, v48, v54
	v_add_f32_e64 v55, v49, v55
	v_pk_add_f32 v[52:53], v[50:51], v[54:55]
	s_nop 0
	v_add_f32_e32 v52, v52, v53
	s_waitcnt lgkmcnt(0)
	v_mfma_f32_32x32x16_bf16 v[4:19], v[138:141], v[36:39], v[4:19]
	ds_bpermute_b32 v53, v110, v52
	s_waitcnt lgkmcnt(0)
	v_add_f32_e32 v52, v52, v53
	v_add_f32_e32 v113, v113, v52
.LBB0_1652:
	s_add_i32 s2, s13, 0xffffffa1
	v_cmp_le_i32_e32 vcc, s2, v104
	s_and_b64 s[2:3], vcc, s[0:1]
	v_cndmask_b32_e64 v36, 0, 1, s[2:3]
	v_cmp_ne_u32_e32 vcc, 0, v36
	s_cbranch_vccz .LBB0_1659
	ds_read_b128 v[36:39], v105 offset:4608
	ds_read_b128 v[40:43], v105 offset:4640
	ds_read_b128 v[44:47], v105 offset:4672
	ds_read_b128 v[48:51], v105 offset:4704
	ds_read_b64_tr_b16 v[126:127], v112 offset:13824
	ds_read_b64_tr_b16 v[128:129], v112 offset:14976
	ds_read_b64_tr_b16 v[130:131], v112 offset:13888
	ds_read_b64_tr_b16 v[132:133], v112 offset:15040
	ds_read_b64_tr_b16 v[134:135], v112 offset:16128
	ds_read_b64_tr_b16 v[136:137], v112 offset:17280
	ds_read_b64_tr_b16 v[138:139], v112 offset:16192
	ds_read_b64_tr_b16 v[140:141], v112 offset:17344
	s_sub_i32 s8, s13, 64
	v_cmp_gt_i32_e32 vcc, s8, v104
	s_and_b64 s[0:1], s[0:1], vcc
	s_waitcnt lgkmcnt(11)
	v_mfma_f32_32x32x16_bf16 v[52:67], v[36:39], v[68:71], 0
	s_waitcnt lgkmcnt(10)
	v_mfma_f32_32x32x16_bf16 v[52:67], v[40:43], v[72:75], v[52:67]
	s_waitcnt lgkmcnt(9)
	v_mfma_f32_32x32x16_bf16 v[52:67], v[44:47], v[76:79], v[52:67]
	s_waitcnt lgkmcnt(8)
	v_mfma_f32_32x32x16_bf16 v[52:67], v[48:51], v[80:83], v[52:67]
	v_cndmask_b32_e64 v36, 0, 1, s[0:1]
	v_cmp_ne_u32_e32 vcc, 0, v36
	s_cbranch_vccz .LBB0_1678
	v_add_u32_e32 v51, s13, v111
	v_add_u32_e32 v37, 0xffffffa1, v51
	v_cmp_le_u32_e32 vcc, v37, v104
	v_add_u32_e32 v38, 0xffffffa3, v51
	v_add_u32_e32 v39, 0xffffffa4, v51
	s_nop 3
	v_cndmask_b32_e32 v36, v231, v52, vcc
	v_cmp_lt_u32_e32 vcc, v37, v104
	v_add_u32_e32 v41, 0xffffffaa, v51
	v_add_u32_e32 v43, 0xffffffac, v51
	v_cndmask_b32_e32 v37, v231, v53, vcc
	v_cmp_le_u32_e32 vcc, v38, v104
	v_max3_f32 v40, v36, s40, v37
	v_add_u32_e32 v45, 0xffffffb2, v51
	v_cndmask_b32_e32 v38, v231, v54, vcc
	v_cmp_le_u32_e32 vcc, v39, v104
	v_add_u32_e32 v47, 0xffffffb4, v51
	v_add_u32_e32 v49, 0xffffffba, v51
	v_cndmask_b32_e32 v39, v231, v55, vcc
	v_max3_f32 v42, v40, v38, v39
	v_add_u32_e32 v40, 0xffffffa9, v51
	v_cmp_le_u32_e32 vcc, v40, v104
	s_nop 1
	v_cndmask_b32_e32 v40, v231, v56, vcc
	v_cmp_le_u32_e32 vcc, v41, v104
	s_nop 1
	v_cndmask_b32_e32 v41, v231, v57, vcc
	v_max3_f32 v44, v42, v40, v41
	v_add_u32_e32 v42, 0xffffffab, v51
	v_cmp_le_u32_e32 vcc, v42, v104
	s_nop 1
	v_cndmask_b32_e32 v42, v231, v58, vcc
	v_cmp_le_u32_e32 vcc, v43, v104
	s_nop 1
	v_cndmask_b32_e32 v43, v231, v59, vcc
	v_max3_f32 v46, v44, v42, v43
	v_add_u32_e32 v44, 0xffffffb1, v51
	v_cmp_le_u32_e32 vcc, v44, v104
	s_nop 1
	v_cndmask_b32_e32 v44, v231, v60, vcc
	v_cmp_le_u32_e32 vcc, v45, v104
	s_nop 1
	v_cndmask_b32_e32 v45, v231, v61, vcc
	v_max3_f32 v48, v46, v44, v45
	v_add_u32_e32 v46, 0xffffffb3, v51
	v_cmp_le_u32_e32 vcc, v46, v104
	s_nop 1
	v_cndmask_b32_e32 v46, v231, v62, vcc
	v_cmp_le_u32_e32 vcc, v47, v104
	s_nop 1
	v_cndmask_b32_e32 v47, v231, v63, vcc
	v_max3_f32 v50, v48, v46, v47
	v_add_u32_e32 v48, 0xffffffb9, v51
	v_cmp_le_u32_e32 vcc, v48, v104
	s_nop 1
	v_cndmask_b32_e32 v48, v231, v64, vcc
	v_cmp_le_u32_e32 vcc, v49, v104
	s_nop 1
	v_cndmask_b32_e32 v49, v231, v65, vcc
	v_max3_f32 v116, v50, v48, v49
	v_add_u32_e32 v50, 0xffffffbb, v51
	v_cmp_le_u32_e32 vcc, v50, v104
	v_add_u32_e32 v51, 0xffffffbc, v51
	s_nop 0
	v_cndmask_b32_e32 v50, v231, v66, vcc
	v_cmp_le_u32_e32 vcc, v51, v104
	s_nop 1
	v_cndmask_b32_e32 v51, v231, v67, vcc
	v_max3_f32 v116, v116, v50, v51
	s_cbranch_execnz .LBB0_1656

; #define LAS __attribute__((address_space(3)))
; DI void tile_online(AState& st, const LAS bf16* Kt, int KP, const LAS bf16* Vt, int VP, const bf16x8 (&qf)[4], int kbase, int lo, int hi, bool flag, int r, int h) {
;     const bool any = flag && (kbase + 31 >= lo) && (kbase <= hi);
;     if (__ballot(any) == 0ull) return;
;     f32x16 s = qk_tile32(Kt, KP, qf, r, h);
;     const bool cut = flag && !((kbase >= lo) && (kbase + 31 <= hi));
;     float mx = -__builtin_inff();
;     if (__ballot(cut) != 0ull) {
;         const unsigned t0 = (unsigned)(kbase + 4 * h - lo), range = (unsigned)(hi - lo);
; #pragma unroll
;         for (int reg = 0; reg < 16; ++reg) { s[reg] = (t0 + (unsigned)((reg & 3) + 8 * (reg >> 2)) <= range) ? s[reg] : -__builtin_inff(); mx = fmaxf(mx, s[reg]); }
;     } else {
; #pragma unroll
;         for (int reg = 0; reg < 16; ++reg) mx = fmaxf(mx, s[reg]);
;     }
; DI void nsa_prompt_unit(Frame& F, int b, int kv, int c) {
;     ...
;             if (two) { const bool fl = (selmask >> (j + 1)) & 1u;
;               tile_online(st, KT1, KTP, VT1, VTP, qf, 64 * j + 64, 0, qpos, fl, r, h);
;               tile_online(st, KT1 + 32 * KTP, KTP, VT1 + 32 * VTP, VTP, qf, 64 * j + 96, 0, qpos, fl, r, h);
.LBB0_1659:
	s_andn2_b64 vcc, exec, s[6:7]
	s_cbranch_vccnz .LBB0_1675
	v_and_b32_e32 v2, 2, v2
	s_sub_i32 s2, s13, 63
	v_cmp_ne_u32_e64 s[0:1], 0, v2
	v_cmp_le_i32_e32 vcc, s2, v104
	s_and_b64 s[2:3], vcc, s[0:1]
	v_cndmask_b32_e64 v2, 0, 1, s[2:3]
	v_cmp_ne_u32_e32 vcc, 0, v2
	s_cbranch_vccz .LBB0_1667
	ds_read_b128 v[36:39], v105 offset:18432
	ds_read_b128 v[40:43], v105 offset:18464
	ds_read_b128 v[44:47], v105 offset:18496
	ds_read_b128 v[48:51], v105 offset:18528
	ds_read_b64_tr_b16 v[126:127], v112 offset:27648
	ds_read_b64_tr_b16 v[128:129], v112 offset:28800
	ds_read_b64_tr_b16 v[130:131], v112 offset:27712
	ds_read_b64_tr_b16 v[132:133], v112 offset:28864
	ds_read_b64_tr_b16 v[134:135], v112 offset:29952
	ds_read_b64_tr_b16 v[136:137], v112 offset:31104
	ds_read_b64_tr_b16 v[138:139], v112 offset:30016
	ds_read_b64_tr_b16 v[140:141], v112 offset:31168
	s_sub_i32 s6, s13, 32
	v_cmp_gt_i32_e32 vcc, s6, v104
	s_and_b64 s[6:7], s[0:1], vcc
	v_cndmask_b32_e64 v2, 0, 1, s[6:7]
	v_cmp_ne_u32_e32 vcc, 0, v2
	s_waitcnt lgkmcnt(11)
	v_mfma_f32_32x32x16_bf16 v[52:67], v[36:39], v[68:71], 0
	s_waitcnt lgkmcnt(10)
	v_mfma_f32_32x32x16_bf16 v[52:67], v[40:43], v[72:75], v[52:67]
	s_waitcnt lgkmcnt(9)
	v_mfma_f32_32x32x16_bf16 v[52:67], v[44:47], v[76:79], v[52:67]
	s_waitcnt lgkmcnt(8)
	v_mfma_f32_32x32x16_bf16 v[52:67], v[48:51], v[80:83], v[52:67]
	s_cbranch_vccz .LBB0_1679
	v_add_u32_e32 v2, s13, v111
	v_subrev_u32_e32 v37, 63, v2
	v_cmp_le_u32_e32 vcc, v37, v104
	v_subrev_u32_e32 v38, 61, v2
	v_subrev_u32_e32 v39, 60, v2
	s_nop 5
	v_cndmask_b32_e32 v36, v231, v52, vcc
	v_cmp_lt_u32_e32 vcc, v37, v104
	v_subrev_u32_e32 v41, 54, v2
	v_subrev_u32_e32 v43, 52, v2
	v_cndmask_b32_e32 v37, v231, v53, vcc
	v_cmp_le_u32_e32 vcc, v38, v104
	v_max3_f32 v40, v36, s40, v37
	v_subrev_u32_e32 v45, 46, v2
	v_cndmask_b32_e32 v38, v231, v54, vcc
	v_cmp_le_u32_e32 vcc, v39, v104
	v_subrev_u32_e32 v47, 44, v2
	v_subrev_u32_e32 v49, 38, v2
	v_cndmask_b32_e32 v39, v231, v55, vcc
	v_max3_f32 v42, v40, v38, v39
	v_subrev_u32_e32 v40, 55, v2
	v_cmp_le_u32_e32 vcc, v40, v104
	s_nop 1
	v_cndmask_b32_e32 v40, v231, v56, vcc
	v_cmp_le_u32_e32 vcc, v41, v104
	s_nop 1
	v_cndmask_b32_e32 v41, v231, v57, vcc
	v_max3_f32 v44, v42, v40, v41
	v_subrev_u32_e32 v42, 53, v2
	v_cmp_le_u32_e32 vcc, v42, v104
	s_nop 1
	v_cndmask_b32_e32 v42, v231, v58, vcc
	v_cmp_le_u32_e32 vcc, v43, v104
	s_nop 1
	v_cndmask_b32_e32 v43, v231, v59, vcc
	v_max3_f32 v46, v44, v42, v43
	v_subrev_u32_e32 v44, 47, v2
	v_cmp_le_u32_e32 vcc, v44, v104
	s_nop 1
	v_cndmask_b32_e32 v44, v231, v60, vcc
	v_cmp_le_u32_e32 vcc, v45, v104
	s_nop 1
	v_cndmask_b32_e32 v45, v231, v61, vcc
	v_max3_f32 v48, v46, v44, v45
	v_subrev_u32_e32 v46, 45, v2
	v_cmp_le_u32_e32 vcc, v46, v104
	s_nop 1
	v_cndmask_b32_e32 v46, v231, v62, vcc
	v_cmp_le_u32_e32 vcc, v47, v104
	s_nop 1
	v_cndmask_b32_e32 v47, v231, v63, vcc
	v_max3_f32 v50, v48, v46, v47
	v_subrev_u32_e32 v48, 39, v2
	v_cmp_le_u32_e32 vcc, v48, v104
	s_nop 1
	v_cndmask_b32_e32 v48, v231, v64, vcc
	v_cmp_le_u32_e32 vcc, v49, v104
	s_nop 1
	v_cndmask_b32_e32 v49, v231, v65, vcc
	v_max3_f32 v116, v50, v48, v49
	v_subrev_u32_e32 v50, 37, v2
	v_cmp_le_u32_e32 vcc, v50, v104
	v_subrev_u32_e32 v2, 36, v2
	s_nop 0
	v_cndmask_b32_e32 v50, v231, v66, vcc
	v_cmp_le_u32_e32 vcc, v2, v104
	s_nop 1
	v_cndmask_b32_e32 v51, v231, v67, vcc
	v_max3_f32 v2, v116, v50, v51
	s_cbranch_execnz .LBB0_1664

; #define LAS __attribute__((address_space(3)))
; DI float fexp2(float x) { return __builtin_amdgcn_exp2f(x); }
; DI float xhalf_sum(float v) { return v + __shfl_xor(v, 32); }
; DI void tile_online(AState& st, const LAS bf16* Kt, int KP, const LAS bf16* Vt, int VP, const bf16x8 (&qf)[4], int kbase, int lo, int hi, bool flag, int r, int h) {
;     const bool any = flag && (kbase + 31 >= lo) && (kbase <= hi);
;     if (__ballot(any) == 0ull) return;
;     f32x16 s = qk_tile32(Kt, KP, qf, r, h);
;     const bool cut = flag && !((kbase >= lo) && (kbase + 31 <= hi));
;     float mx = -__builtin_inff();
;     if (__ballot(cut) != 0ull) {
;         const unsigned t0 = (unsigned)(kbase + 4 * h - lo), range = (unsigned)(hi - lo);
; #pragma unroll
;         for (int reg = 0; reg < 16; ++reg) { s[reg] = (t0 + (unsigned)((reg & 3) + 8 * (reg >> 2)) <= range) ? s[reg] : -__builtin_inff(); mx = fmaxf(mx, s[reg]); }
;     } else {
; #pragma unroll
;         for (int reg = 0; reg < 16; ++reg) mx = fmaxf(mx, s[reg]);
;     }
;     ...
;     const float mn = st.m;
;     const float bias = any ? -mn * LOG2E : -__builtin_inff();
;     f32x2 sum2 = {0.f, 0.f}; const f32x2 b2 = {bias, bias}, l2 = {LOG2E, LOG2E};
; #pragma unroll
;     for (int reg = 0; reg < 16; reg += 2) { f32x2 t = {s[reg], s[reg + 1]}; t = __builtin_elementwise_fma(t, l2, b2);
;         t[0] = fexp2(t[0]); t[1] = fexp2(t[1]); s[reg] = t[0]; s[reg + 1] = t[1]; sum2 = sum2 + t; }
;     st.l += xhalf_sum(sum2[0] + sum2[1]);
;     pv_tile32(st.o0, st.o1, Vt, VP, s, r + 32 * h);
; }
.LBB0_1666:
	v_mul_f32_e32 v2, 0xbfb8aa3b, v115
	v_cndmask_b32_e64 v2, v231, v2, s[2:3]
	v_pk_fma_f32 v[36:37], v[36:37], s[38:39], v[2:3] op_sel_hi:[1,0,0]
	v_pk_fma_f32 v[38:39], v[38:39], s[38:39], v[2:3] op_sel_hi:[1,0,0]
	v_exp_f32_e32 v36, v36
	v_exp_f32_e32 v37, v37
	v_exp_f32_e32 v38, v38
	v_exp_f32_e32 v39, v39
	v_pk_fma_f32 v[40:41], v[40:41], s[38:39], v[2:3] op_sel_hi:[1,0,0]
	v_pk_fma_f32 v[42:43], v[42:43], s[38:39], v[2:3] op_sel_hi:[1,0,0]
	v_exp_f32_e32 v40, v40
	v_exp_f32_e32 v41, v41
	v_exp_f32_e32 v42, v42
	v_exp_f32_e32 v43, v43
	v_pk_add_f32 v[52:53], v[36:37], 0 op_sel_hi:[1,0]
	v_cvt_pk_bf16_f32 v36, v36, v37
	v_pk_add_f32 v[52:53], v[38:39], v[52:53]
	v_cvt_pk_bf16_f32 v37, v38, v39
	v_pk_add_f32 v[52:53], v[40:41], v[52:53]
	v_cvt_pk_bf16_f32 v38, v40, v41
	v_pk_add_f32 v[52:53], v[42:43], v[52:53]
	v_cvt_pk_bf16_f32 v39, v42, v43
	s_waitcnt lgkmcnt(0)
	v_mfma_f32_32x32x16_bf16 v[20:35], v[126:129], v[36:39], v[20:35]
	v_fma_f32 v44, v44, s38, v2
	v_fma_f32 v45, v45, s38, v2
	v_fma_f32 v46, v46, s38, v2
	v_fma_f32 v47, v47, s38, v2
	v_pk_fma_f32 v[48:49], v[48:49], s[38:39], v[2:3] op_sel_hi:[1,0,0]
	v_pk_fma_f32 v[50:51], v[50:51], s[38:39], v[2:3] op_sel_hi:[1,0,0]
	v_exp_f32_e32 v44, v44
	v_exp_f32_e32 v45, v45
	v_exp_f32_e32 v46, v46
	v_exp_f32_e32 v47, v47
	v_exp_f32_e32 v48, v48
	v_exp_f32_e32 v49, v49
	v_exp_f32_e32 v50, v50
	v_exp_f32_e32 v51, v51
	s_waitcnt lgkmcnt(0)
	v_mfma_f32_32x32x16_bf16 v[4:19], v[130:133], v[36:39], v[4:19]
	v_cvt_pk_bf16_f32 v36, v44, v45
	v_cvt_pk_bf16_f32 v37, v46, v47
	v_cvt_pk_bf16_f32 v38, v48, v49
	v_cvt_pk_bf16_f32 v39, v50, v51
	v_pk_add_f32 v[52:53], v[44:45], v[52:53]
	s_waitcnt lgkmcnt(0)
	v_mfma_f32_32x32x16_bf16 v[20:35], v[134:137], v[36:39], v[20:35]
	v_add_f32_e64 v52, v46, v52
	v_add_f32_e64 v53, v47, v53
	v_add_f32_e64 v52, v48, v52
	v_add_f32_e64 v53, v49, v53
	v_pk_add_f32 v[52:53], v[50:51], v[52:53]
	s_nop 0
	v_add_f32_e32 v2, v52, v53
	s_waitcnt lgkmcnt(0)
	v_mfma_f32_32x32x16_bf16 v[4:19], v[138:141], v[36:39], v[4:19]
	ds_bpermute_b32 v52, v110, v2
	s_waitcnt lgkmcnt(0)
	v_add_f32_e32 v2, v2, v52
	v_add_f32_e32 v113, v113, v2
.LBB0_1667:
	s_sub_i32 s2, s13, 31
	v_cmp_le_i32_e32 vcc, s2, v104
	s_and_b64 s[2:3], vcc, s[0:1]
	v_cndmask_b32_e64 v2, 0, 1, s[2:3]
	v_cmp_ne_u32_e32 vcc, 0, v2
	s_cbranch_vccz .LBB0_1674
	ds_read_b128 v[36:39], v105 offset:23040
	ds_read_b128 v[40:43], v105 offset:23072
	ds_read_b128 v[44:47], v105 offset:23104
	ds_read_b128 v[48:51], v105 offset:23136
	ds_read_b64_tr_b16 v[126:127], v112 offset:32256
	ds_read_b64_tr_b16 v[128:129], v112 offset:33408
	ds_read_b64_tr_b16 v[130:131], v112 offset:32320
	ds_read_b64_tr_b16 v[132:133], v112 offset:33472
	ds_read_b64_tr_b16 v[134:135], v112 offset:34560
	ds_read_b64_tr_b16 v[136:137], v112 offset:35712
	ds_read_b64_tr_b16 v[138:139], v112 offset:34624
	ds_read_b64_tr_b16 v[140:141], v112 offset:35776
	v_cmp_gt_i32_e32 vcc, s13, v104
	s_and_b64 s[0:1], s[0:1], vcc
	v_cndmask_b32_e64 v2, 0, 1, s[0:1]
	v_cmp_ne_u32_e32 vcc, 0, v2
	s_waitcnt lgkmcnt(11)
	v_mfma_f32_32x32x16_bf16 v[52:67], v[36:39], v[68:71], 0
	s_waitcnt lgkmcnt(10)
	v_mfma_f32_32x32x16_bf16 v[52:67], v[40:43], v[72:75], v[52:67]
	s_waitcnt lgkmcnt(9)
	v_mfma_f32_32x32x16_bf16 v[52:67], v[44:47], v[76:79], v[52:67]
	s_waitcnt lgkmcnt(8)
	v_mfma_f32_32x32x16_bf16 v[52:67], v[48:51], v[80:83], v[52:67]
	s_cbranch_vccz .LBB0_1680
	v_add_u32_e32 v2, s13, v111
	v_subrev_u32_e32 v37, 31, v2
	v_cmp_le_u32_e32 vcc, v37, v104
	v_subrev_u32_e32 v38, 29, v2
	v_subrev_u32_e32 v39, 28, v2
	s_nop 5
	v_cndmask_b32_e32 v36, v231, v52, vcc
	v_cmp_lt_u32_e32 vcc, v37, v104
	v_subrev_u32_e32 v41, 22, v2
	v_subrev_u32_e32 v43, 20, v2
	v_cndmask_b32_e32 v37, v231, v53, vcc
	v_cmp_le_u32_e32 vcc, v38, v104
	v_max3_f32 v40, v36, s40, v37
	v_add_u32_e32 v45, -14, v2
	v_cndmask_b32_e32 v38, v231, v54, vcc
	v_cmp_le_u32_e32 vcc, v39, v104
	v_add_u32_e32 v47, -12, v2
	v_add_u32_e32 v49, -6, v2
	v_cndmask_b32_e32 v39, v231, v55, vcc
	v_max3_f32 v42, v40, v38, v39
	v_subrev_u32_e32 v40, 23, v2
	v_cmp_le_u32_e32 vcc, v40, v104
	s_nop 1
	v_cndmask_b32_e32 v40, v231, v56, vcc
	v_cmp_le_u32_e32 vcc, v41, v104
	s_nop 1
	v_cndmask_b32_e32 v41, v231, v57, vcc
	v_max3_f32 v44, v42, v40, v41
	v_subrev_u32_e32 v42, 21, v2
	v_cmp_le_u32_e32 vcc, v42, v104
	s_nop 1
	v_cndmask_b32_e32 v42, v231, v58, vcc
	v_cmp_le_u32_e32 vcc, v43, v104
	s_nop 1
	v_cndmask_b32_e32 v43, v231, v59, vcc
	v_max3_f32 v46, v44, v42, v43
	v_add_u32_e32 v44, -15, v2
	v_cmp_le_u32_e32 vcc, v44, v104
	s_nop 1
	v_cndmask_b32_e32 v44, v231, v60, vcc
	v_cmp_le_u32_e32 vcc, v45, v104
	s_nop 1
	v_cndmask_b32_e32 v45, v231, v61, vcc
	v_max3_f32 v48, v46, v44, v45
	v_add_u32_e32 v46, -13, v2
	v_cmp_le_u32_e32 vcc, v46, v104
	s_nop 1
	v_cndmask_b32_e32 v46, v231, v62, vcc
	v_cmp_le_u32_e32 vcc, v47, v104
	s_nop 1
	v_cndmask_b32_e32 v47, v231, v63, vcc
	v_max3_f32 v50, v48, v46, v47
	v_add_u32_e32 v48, -7, v2
	v_cmp_le_u32_e32 vcc, v48, v104
	s_nop 1
	v_cndmask_b32_e32 v48, v231, v64, vcc
	v_cmp_le_u32_e32 vcc, v49, v104
	s_nop 1
	v_cndmask_b32_e32 v49, v231, v65, vcc
	v_max3_f32 v116, v50, v48, v49
	v_add_u32_e32 v50, -5, v2
	v_cmp_le_u32_e32 vcc, v50, v104
	v_add_u32_e32 v2, -4, v2
	s_nop 0
	v_cndmask_b32_e32 v50, v231, v66, vcc
	v_cmp_le_u32_e32 vcc, v2, v104
	s_nop 1
	v_cndmask_b32_e32 v51, v231, v67, vcc
	v_max3_f32 v2, v116, v50, v51
	s_cbranch_execnz .LBB0_1671

; DI float fexp2(float x) { return __builtin_amdgcn_exp2f(x); }
; DI float xhalf_sum(float v) { return v + __shfl_xor(v, 32); }
; DI void tile_online(AState& st, const LAS bf16* Kt, int KP, const LAS bf16* Vt, int VP, const bf16x8 (&qf)[4], int kbase, int lo, int hi, bool flag, int r, int h) {
;     ...
;     const float mn = st.m;
;     const float bias = any ? -mn * LOG2E : -__builtin_inff();
;     f32x2 sum2 = {0.f, 0.f}; const f32x2 b2 = {bias, bias}, l2 = {LOG2E, LOG2E};
; #pragma unroll
;     for (int reg = 0; reg < 16; reg += 2) { f32x2 t = {s[reg], s[reg + 1]}; t = __builtin_elementwise_fma(t, l2, b2);
;         t[0] = fexp2(t[0]); t[1] = fexp2(t[1]); s[reg] = t[0]; s[reg + 1] = t[1]; sum2 = sum2 + t; }
;     st.l += xhalf_sum(sum2[0] + sum2[1]);
;     pv_tile32(st.o0, st.o1, Vt, VP, s, r + 32 * h);
; }
.LBB0_1684:
	v_mul_f32_e32 v2, 0xbfb8aa3b, v116
	v_cndmask_b32_e64 v2, v231, v2, s[0:1]
	v_pk_fma_f32 v[36:37], v[36:37], s[38:39], v[2:3] op_sel_hi:[1,0,0]
	v_pk_fma_f32 v[38:39], v[38:39], s[38:39], v[2:3] op_sel_hi:[1,0,0]
	v_exp_f32_e32 v36, v36
	v_exp_f32_e32 v37, v37
	v_exp_f32_e32 v38, v38
	v_exp_f32_e32 v39, v39
	v_pk_fma_f32 v[40:41], v[40:41], s[38:39], v[2:3] op_sel_hi:[1,0,0]
	v_pk_fma_f32 v[42:43], v[42:43], s[38:39], v[2:3] op_sel_hi:[1,0,0]
	v_exp_f32_e32 v40, v40
	v_exp_f32_e32 v41, v41
	v_exp_f32_e32 v42, v42
	v_exp_f32_e32 v43, v43
	v_pk_add_f32 v[52:53], v[36:37], 0 op_sel_hi:[1,0]
	v_cvt_pk_bf16_f32 v36, v36, v37
	v_pk_add_f32 v[52:53], v[38:39], v[52:53]
	v_cvt_pk_bf16_f32 v37, v38, v39
	v_pk_add_f32 v[52:53], v[40:41], v[52:53]
	v_cvt_pk_bf16_f32 v38, v40, v41
	v_pk_add_f32 v[52:53], v[42:43], v[52:53]
	v_cvt_pk_bf16_f32 v39, v42, v43
	s_waitcnt lgkmcnt(0)
	v_mfma_f32_32x32x16_bf16 v[20:35], v[126:129], v[36:39], v[20:35]
	v_fma_f32 v44, v44, s38, v2
	v_fma_f32 v45, v45, s38, v2
	v_fma_f32 v46, v46, s38, v2
	v_fma_f32 v47, v47, s38, v2
	v_pk_fma_f32 v[48:49], v[48:49], s[38:39], v[2:3] op_sel_hi:[1,0,0]
	v_pk_fma_f32 v[50:51], v[50:51], s[38:39], v[2:3] op_sel_hi:[1,0,0]
	v_exp_f32_e32 v44, v44
	v_exp_f32_e32 v45, v45
	v_exp_f32_e32 v46, v46
	v_exp_f32_e32 v47, v47
	v_exp_f32_e32 v48, v48
	v_exp_f32_e32 v49, v49
	v_exp_f32_e32 v50, v50
	v_exp_f32_e32 v51, v51
	s_waitcnt lgkmcnt(0)
	v_mfma_f32_32x32x16_bf16 v[4:19], v[130:133], v[36:39], v[4:19]
	v_cvt_pk_bf16_f32 v36, v44, v45
	v_cvt_pk_bf16_f32 v37, v46, v47
	v_cvt_pk_bf16_f32 v38, v48, v49
	v_cvt_pk_bf16_f32 v39, v50, v51
	v_pk_add_f32 v[52:53], v[44:45], v[52:53]
	s_waitcnt lgkmcnt(0)
	v_mfma_f32_32x32x16_bf16 v[20:35], v[134:137], v[36:39], v[20:35]
	v_add_f32_e64 v52, v46, v52
	v_add_f32_e64 v53, v47, v53
	v_add_f32_e64 v52, v48, v52
	v_add_f32_e64 v53, v49, v53
	v_pk_add_f32 v[52:53], v[50:51], v[52:53]
	s_nop 0
	v_add_f32_e32 v2, v52, v53
	s_waitcnt lgkmcnt(0)
	v_mfma_f32_32x32x16_bf16 v[4:19], v[138:141], v[36:39], v[4:19]
	ds_bpermute_b32 v52, v110, v2
	s_waitcnt lgkmcnt(0)
	v_add_f32_e32 v2, v2, v52
	v_add_f32_e32 v111, v111, v2

; #define LAS __attribute__((address_space(3)))
; DI void tile_online(AState& st, const LAS bf16* Kt, int KP, const LAS bf16* Vt, int VP, const bf16x8 (&qf)[4], int kbase, int lo, int hi, bool flag, int r, int h) {
;     const bool any = flag && (kbase + 31 >= lo) && (kbase <= hi);
;     if (__ballot(any) == 0ull) return;
;     f32x16 s = qk_tile32(Kt, KP, qf, r, h);
;     const bool cut = flag && !((kbase >= lo) && (kbase + 31 <= hi));
;     float mx = -__builtin_inff();
;     if (__ballot(cut) != 0ull) {
;         const unsigned t0 = (unsigned)(kbase + 4 * h - lo), range = (unsigned)(hi - lo);
; #pragma unroll
;         for (int reg = 0; reg < 16; ++reg) { s[reg] = (t0 + (unsigned)((reg & 3) + 8 * (reg >> 2)) <= range) ? s[reg] : -__builtin_inff(); mx = fmaxf(mx, s[reg]); }
;     } else {
; #pragma unroll
;         for (int reg = 0; reg < 16; ++reg) mx = fmaxf(mx, s[reg]);
;     }
; DI void nsa_prompt_unit(Frame& F, int b, int kv, int c) {
;     ...
;             tile_online(st, KT0, KTP, VT0, VTP, qf, 64 * j, qpos - 511, qpos, true, r, h);
;             tile_online(st, KT0 + 32 * KTP, KTP, VT0 + 32 * VTP, VTP, qf, 64 * j + 32, qpos - 511, qpos, true, r, h);
;             if (two) {
;               tile_online(st, KT1, KTP, VT1, VTP, qf, 64 * j + 64, qpos - 511, qpos, true, r, h);
;               tile_online(st, KT1 + 32 * KTP, KTP, VT1 + 32 * VTP, VTP, qf, 64 * j + 96, qpos - 511, qpos, true, r, h);
.LBB0_1693:
	s_add_i32 s2, s6, 31
	v_cmp_ge_i32_e32 vcc, s2, v114
	v_cmp_le_i32_e64 s[0:1], s6, v104
	s_and_b64 s[0:1], s[0:1], vcc
	s_mov_b64 vcc, s[0:1]
	s_cbranch_vccz .LBB0_1700
	ds_read_b128 v[36:39], v105
	ds_read_b128 v[40:43], v105 offset:32
	ds_read_b128 v[44:47], v105 offset:64
	ds_read_b128 v[48:51], v105 offset:96
	ds_read_b64_tr_b16 v[126:127], v112 offset:9216
	ds_read_b64_tr_b16 v[128:129], v112 offset:10368
	ds_read_b64_tr_b16 v[130:131], v112 offset:9280
	ds_read_b64_tr_b16 v[132:133], v112 offset:10432
	ds_read_b64_tr_b16 v[134:135], v112 offset:11520
	ds_read_b64_tr_b16 v[136:137], v112 offset:12672
	ds_read_b64_tr_b16 v[138:139], v112 offset:11584
	ds_read_b64_tr_b16 v[140:141], v112 offset:12736
	v_cmp_lt_i32_e32 vcc, s6, v114
	v_cmp_gt_i32_e64 s[2:3], s2, v104
	s_or_b64 vcc, vcc, s[2:3]
	s_waitcnt lgkmcnt(11)
	v_mfma_f32_32x32x16_bf16 v[52:67], v[36:39], v[68:71], 0
	s_waitcnt lgkmcnt(10)
	v_mfma_f32_32x32x16_bf16 v[52:67], v[40:43], v[72:75], v[52:67]
	s_waitcnt lgkmcnt(9)
	v_mfma_f32_32x32x16_bf16 v[52:67], v[44:47], v[76:79], v[52:67]
	s_waitcnt lgkmcnt(8)
	v_mfma_f32_32x32x16_bf16 v[52:67], v[48:51], v[80:83], v[52:67]
	s_cbranch_vccz .LBB0_1721
	v_add_u32_e32 v2, s6, v115
	v_add_u32_e32 v36, 0x1ff, v2
	v_cmp_gt_u32_e32 vcc, s31, v36
	v_add_u32_e32 v38, 1, v2
	v_add_u32_e32 v39, 2, v2
	s_nop 5
	v_cndmask_b32_e32 v36, v231, v52, vcc
	v_cmp_lt_u32_e32 vcc, s41, v2
	v_add_u32_e32 v41, 8, v2
	v_add_u32_e32 v43, 10, v2
	v_cndmask_b32_e32 v37, v231, v53, vcc
	v_cmp_lt_u32_e32 vcc, s41, v38
	v_max3_f32 v40, v36, s40, v37
	v_add_u32_e32 v45, 16, v2
	v_cndmask_b32_e32 v38, v231, v54, vcc
	v_cmp_lt_u32_e32 vcc, s41, v39
	v_add_u32_e32 v47, 18, v2
	v_add_u32_e32 v49, 24, v2
	v_cndmask_b32_e32 v39, v231, v55, vcc
	v_max3_f32 v42, v40, v38, v39
	v_add_u32_e32 v40, 7, v2
	v_cmp_lt_u32_e32 vcc, s41, v40
	s_nop 1
	v_cndmask_b32_e32 v40, v231, v56, vcc
	v_cmp_lt_u32_e32 vcc, s41, v41
	s_nop 1
	v_cndmask_b32_e32 v41, v231, v57, vcc
	v_max3_f32 v44, v42, v40, v41
	v_add_u32_e32 v42, 9, v2
	v_cmp_lt_u32_e32 vcc, s41, v42
	s_nop 1
	v_cndmask_b32_e32 v42, v231, v58, vcc
	v_cmp_lt_u32_e32 vcc, s41, v43
	s_nop 1
	v_cndmask_b32_e32 v43, v231, v59, vcc
	v_max3_f32 v46, v44, v42, v43
	v_add_u32_e32 v44, 15, v2
	v_cmp_lt_u32_e32 vcc, s41, v44
	s_nop 1
	v_cndmask_b32_e32 v44, v231, v60, vcc
	v_cmp_lt_u32_e32 vcc, s41, v45
	s_nop 1
	v_cndmask_b32_e32 v45, v231, v61, vcc
	v_max3_f32 v48, v46, v44, v45
	v_add_u32_e32 v46, 17, v2
	v_cmp_lt_u32_e32 vcc, s41, v46
	s_nop 1
	v_cndmask_b32_e32 v46, v231, v62, vcc
	v_cmp_lt_u32_e32 vcc, s41, v47
	s_nop 1
	v_cndmask_b32_e32 v47, v231, v63, vcc
	v_max3_f32 v50, v48, v46, v47
	v_add_u32_e32 v48, 23, v2
	v_cmp_lt_u32_e32 vcc, s41, v48
	s_nop 1
	v_cndmask_b32_e32 v48, v231, v64, vcc
	v_cmp_lt_u32_e32 vcc, s41, v49
	s_nop 1
	v_cndmask_b32_e32 v49, v231, v65, vcc
	v_max3_f32 v117, v50, v48, v49
	v_add_u32_e32 v50, 25, v2
	v_cmp_lt_u32_e32 vcc, s41, v50
	v_add_u32_e32 v2, 26, v2
	s_nop 0
	v_cndmask_b32_e32 v50, v231, v66, vcc
	v_cmp_lt_u32_e32 vcc, s41, v2
	s_nop 1
	v_cndmask_b32_e32 v51, v231, v67, vcc
	v_max3_f32 v2, v117, v50, v51
	s_cbranch_execnz .LBB0_1697

; #define LAS __attribute__((address_space(3)))
; DI void tile_online(AState& st, const LAS bf16* Kt, int KP, const LAS bf16* Vt, int VP, const bf16x8 (&qf)[4], int kbase, int lo, int hi, bool flag, int r, int h) {
;     const bool any = flag && (kbase + 31 >= lo) && (kbase <= hi);
;     if (__ballot(any) == 0ull) return;
;     f32x16 s = qk_tile32(Kt, KP, qf, r, h);
;     const bool cut = flag && !((kbase >= lo) && (kbase + 31 <= hi));
;     float mx = -__builtin_inff();
;     if (__ballot(cut) != 0ull) {
;         const unsigned t0 = (unsigned)(kbase + 4 * h - lo), range = (unsigned)(hi - lo);
; #pragma unroll
;         for (int reg = 0; reg < 16; ++reg) { s[reg] = (t0 + (unsigned)((reg & 3) + 8 * (reg >> 2)) <= range) ? s[reg] : -__builtin_inff(); mx = fmaxf(mx, s[reg]); }
;     } else {
; #pragma unroll
;         for (int reg = 0; reg < 16; ++reg) mx = fmaxf(mx, s[reg]);
;     }
; DI void nsa_prompt_unit(Frame& F, int b, int kv, int c) {
;     ...
;             tile_online(st, KT0, KTP, VT0, VTP, qf, 64 * j, qpos - 511, qpos, true, r, h);
;             tile_online(st, KT0 + 32 * KTP, KTP, VT0 + 32 * VTP, VTP, qf, 64 * j + 32, qpos - 511, qpos, true, r, h);
;             if (two) {
;               tile_online(st, KT1, KTP, VT1, VTP, qf, 64 * j + 64, qpos - 511, qpos, true, r, h);
;               tile_online(st, KT1 + 32 * KTP, KTP, VT1 + 32 * VTP, VTP, qf, 64 * j + 96, qpos - 511, qpos, true, r, h);
.LBB0_1700:
	s_add_i32 s2, s6, 32
	s_add_i32 s3, s6, 63
	v_cmp_ge_i32_e32 vcc, s3, v114
	v_cmp_le_i32_e64 s[0:1], s2, v104
	s_and_b64 s[0:1], s[0:1], vcc
	s_mov_b64 vcc, s[0:1]
	s_cbranch_vccz .LBB0_1707
	ds_read_b128 v[36:39], v105 offset:4608
	ds_read_b128 v[40:43], v105 offset:4640
	ds_read_b128 v[44:47], v105 offset:4672
	ds_read_b128 v[48:51], v105 offset:4704
	ds_read_b64_tr_b16 v[126:127], v112 offset:13824
	ds_read_b64_tr_b16 v[128:129], v112 offset:14976
	ds_read_b64_tr_b16 v[130:131], v112 offset:13888
	ds_read_b64_tr_b16 v[132:133], v112 offset:15040
	ds_read_b64_tr_b16 v[134:135], v112 offset:16128
	ds_read_b64_tr_b16 v[136:137], v112 offset:17280
	ds_read_b64_tr_b16 v[138:139], v112 offset:16192
	ds_read_b64_tr_b16 v[140:141], v112 offset:17344
	v_cmp_lt_i32_e32 vcc, s2, v114
	v_cmp_gt_i32_e64 s[2:3], s3, v104
	s_or_b64 vcc, vcc, s[2:3]
	s_waitcnt lgkmcnt(11)
	v_mfma_f32_32x32x16_bf16 v[52:67], v[36:39], v[68:71], 0
	s_waitcnt lgkmcnt(10)
	v_mfma_f32_32x32x16_bf16 v[52:67], v[40:43], v[72:75], v[52:67]
	s_waitcnt lgkmcnt(9)
	v_mfma_f32_32x32x16_bf16 v[52:67], v[44:47], v[76:79], v[52:67]
	s_waitcnt lgkmcnt(8)
	v_mfma_f32_32x32x16_bf16 v[52:67], v[48:51], v[80:83], v[52:67]
	s_cbranch_vccz .LBB0_1722
	v_add_u32_e32 v2, s6, v115
	v_add_u32_e32 v36, 0x21f, v2
	v_cmp_gt_u32_e32 vcc, s31, v36
	v_add_u32_e32 v37, 32, v2
	v_add_u32_e32 v38, 33, v2
	s_nop 5
	v_cndmask_b32_e32 v36, v231, v52, vcc
	v_cmp_lt_u32_e32 vcc, s41, v37
	v_add_u32_e32 v39, 34, v2
	v_add_u32_e32 v41, 40, v2
	v_cndmask_b32_e32 v37, v231, v53, vcc
	v_cmp_lt_u32_e32 vcc, s41, v38
	v_max3_f32 v40, v36, s40, v37
	v_add_u32_e32 v43, 42, v2
	v_cndmask_b32_e32 v38, v231, v54, vcc
	v_cmp_lt_u32_e32 vcc, s41, v39
	v_add_u32_e32 v45, 48, v2
	v_add_u32_e32 v47, 50, v2
	v_cndmask_b32_e32 v39, v231, v55, vcc
	v_max3_f32 v42, v40, v38, v39
	v_add_u32_e32 v40, 39, v2
	v_cmp_lt_u32_e32 vcc, s41, v40
	v_add_u32_e32 v49, 56, v2
	s_nop 0
	v_cndmask_b32_e32 v40, v231, v56, vcc
	v_cmp_lt_u32_e32 vcc, s41, v41
	s_nop 1
	v_cndmask_b32_e32 v41, v231, v57, vcc
	v_max3_f32 v44, v42, v40, v41
	v_add_u32_e32 v42, 41, v2
	v_cmp_lt_u32_e32 vcc, s41, v42
	s_nop 1
	v_cndmask_b32_e32 v42, v231, v58, vcc
	v_cmp_lt_u32_e32 vcc, s41, v43
	s_nop 1
	v_cndmask_b32_e32 v43, v231, v59, vcc
	v_max3_f32 v46, v44, v42, v43
	v_add_u32_e32 v44, 47, v2
	v_cmp_lt_u32_e32 vcc, s41, v44
	s_nop 1
	v_cndmask_b32_e32 v44, v231, v60, vcc
	v_cmp_lt_u32_e32 vcc, s41, v45
	s_nop 1
	v_cndmask_b32_e32 v45, v231, v61, vcc
	v_max3_f32 v48, v46, v44, v45
	v_add_u32_e32 v46, 49, v2
	v_cmp_lt_u32_e32 vcc, s41, v46
	s_nop 1
	v_cndmask_b32_e32 v46, v231, v62, vcc
	v_cmp_lt_u32_e32 vcc, s41, v47
	s_nop 1
	v_cndmask_b32_e32 v47, v231, v63, vcc
	v_max3_f32 v50, v48, v46, v47
	v_add_u32_e32 v48, 55, v2
	v_cmp_lt_u32_e32 vcc, s41, v48
	s_nop 1
	v_cndmask_b32_e32 v48, v231, v64, vcc
	v_cmp_lt_u32_e32 vcc, s41, v49
	s_nop 1
	v_cndmask_b32_e32 v49, v231, v65, vcc
	v_max3_f32 v117, v50, v48, v49
	v_add_u32_e32 v50, 57, v2
	v_cmp_lt_u32_e32 vcc, s41, v50
	v_add_u32_e32 v2, 58, v2
	s_nop 0
	v_cndmask_b32_e32 v50, v231, v66, vcc
	v_cmp_lt_u32_e32 vcc, s41, v2
	s_nop 1
	v_cndmask_b32_e32 v51, v231, v67, vcc
	v_max3_f32 v2, v117, v50, v51
	s_cbranch_execnz .LBB0_1704

; #define LAS __attribute__((address_space(3)))
; DI void tile_online(AState& st, const LAS bf16* Kt, int KP, const LAS bf16* Vt, int VP, const bf16x8 (&qf)[4], int kbase, int lo, int hi, bool flag, int r, int h) {
;     const bool any = flag && (kbase + 31 >= lo) && (kbase <= hi);
;     if (__ballot(any) == 0ull) return;
;     f32x16 s = qk_tile32(Kt, KP, qf, r, h);
;     const bool cut = flag && !((kbase >= lo) && (kbase + 31 <= hi));
;     float mx = -__builtin_inff();
;     if (__ballot(cut) != 0ull) {
;         const unsigned t0 = (unsigned)(kbase + 4 * h - lo), range = (unsigned)(hi - lo);
; #pragma unroll
;         for (int reg = 0; reg < 16; ++reg) { s[reg] = (t0 + (unsigned)((reg & 3) + 8 * (reg >> 2)) <= range) ? s[reg] : -__builtin_inff(); mx = fmaxf(mx, s[reg]); }
;     } else {
; #pragma unroll
;         for (int reg = 0; reg < 16; ++reg) mx = fmaxf(mx, s[reg]);
;     }
; DI void nsa_prompt_unit(Frame& F, int b, int kv, int c) {
;     ...
;             if (two) {
;               tile_online(st, KT1, KTP, VT1, VTP, qf, 64 * j + 64, qpos - 511, qpos, true, r, h);
;               tile_online(st, KT1 + 32 * KTP, KTP, VT1 + 32 * VTP, VTP, qf, 64 * j + 96, qpos - 511, qpos, true, r, h);
.LBB0_1707:
	s_andn2_b64 vcc, exec, s[4:5]
	s_cbranch_vccnz .LBB0_1686
	s_add_i32 s2, s6, 64
	s_add_i32 s3, s6, 0x5f
	v_cmp_ge_i32_e32 vcc, s3, v114
	v_cmp_le_i32_e64 s[0:1], s2, v104
	s_and_b64 s[0:1], s[0:1], vcc
	s_mov_b64 vcc, s[0:1]
	s_cbranch_vccz .LBB0_1715
	ds_read_b128 v[36:39], v105 offset:18432
	ds_read_b128 v[40:43], v105 offset:18464
	ds_read_b128 v[44:47], v105 offset:18496
	ds_read_b128 v[48:51], v105 offset:18528
	ds_read_b64_tr_b16 v[126:127], v112 offset:27648
	ds_read_b64_tr_b16 v[128:129], v112 offset:28800
	ds_read_b64_tr_b16 v[130:131], v112 offset:27712
	ds_read_b64_tr_b16 v[132:133], v112 offset:28864
	ds_read_b64_tr_b16 v[134:135], v112 offset:29952
	ds_read_b64_tr_b16 v[136:137], v112 offset:31104
	ds_read_b64_tr_b16 v[138:139], v112 offset:30016
	ds_read_b64_tr_b16 v[140:141], v112 offset:31168
	v_cmp_lt_i32_e32 vcc, s2, v114
	v_cmp_gt_i32_e64 s[2:3], s3, v104
	s_or_b64 vcc, vcc, s[2:3]
	s_waitcnt lgkmcnt(11)
	v_mfma_f32_32x32x16_bf16 v[52:67], v[36:39], v[68:71], 0
	s_waitcnt lgkmcnt(10)
	v_mfma_f32_32x32x16_bf16 v[52:67], v[40:43], v[72:75], v[52:67]
	s_waitcnt lgkmcnt(9)
	v_mfma_f32_32x32x16_bf16 v[52:67], v[44:47], v[76:79], v[52:67]
	s_waitcnt lgkmcnt(8)
	v_mfma_f32_32x32x16_bf16 v[52:67], v[48:51], v[80:83], v[52:67]
	s_cbranch_vccz .LBB0_1723
	v_add_u32_e32 v2, s6, v115
	v_add_u32_e32 v36, 0x23f, v2
	v_cmp_gt_u32_e32 vcc, s31, v36
	v_add_u32_e32 v37, 64, v2
	v_add_u32_e32 v38, 0x41, v2
	s_nop 5
	v_cndmask_b32_e32 v36, v231, v52, vcc
	v_cmp_lt_u32_e32 vcc, s41, v37
	v_add_u32_e32 v39, 0x42, v2
	v_add_u32_e32 v41, 0x48, v2
	v_cndmask_b32_e32 v37, v231, v53, vcc
	v_cmp_lt_u32_e32 vcc, s41, v38
	v_max3_f32 v40, v36, s40, v37
	v_add_u32_e32 v43, 0x4a, v2
	v_cndmask_b32_e32 v38, v231, v54, vcc
	v_cmp_lt_u32_e32 vcc, s41, v39
	v_add_u32_e32 v45, 0x50, v2
	v_add_u32_e32 v47, 0x52, v2
	v_cndmask_b32_e32 v39, v231, v55, vcc
	v_max3_f32 v42, v40, v38, v39
	v_add_u32_e32 v40, 0x47, v2
	v_cmp_lt_u32_e32 vcc, s41, v40
	v_add_u32_e32 v49, 0x58, v2
	s_nop 0
	v_cndmask_b32_e32 v40, v231, v56, vcc
	v_cmp_lt_u32_e32 vcc, s41, v41
	s_nop 1
	v_cndmask_b32_e32 v41, v231, v57, vcc
	v_max3_f32 v44, v42, v40, v41
	v_add_u32_e32 v42, 0x49, v2
	v_cmp_lt_u32_e32 vcc, s41, v42
	s_nop 1
	v_cndmask_b32_e32 v42, v231, v58, vcc
	v_cmp_lt_u32_e32 vcc, s41, v43
	s_nop 1
	v_cndmask_b32_e32 v43, v231, v59, vcc
	v_max3_f32 v46, v44, v42, v43
	v_add_u32_e32 v44, 0x4f, v2
	v_cmp_lt_u32_e32 vcc, s41, v44
	s_nop 1
	v_cndmask_b32_e32 v44, v231, v60, vcc
	v_cmp_lt_u32_e32 vcc, s41, v45
	s_nop 1
	v_cndmask_b32_e32 v45, v231, v61, vcc
	v_max3_f32 v48, v46, v44, v45
	v_add_u32_e32 v46, 0x51, v2
	v_cmp_lt_u32_e32 vcc, s41, v46
	s_nop 1
	v_cndmask_b32_e32 v46, v231, v62, vcc
	v_cmp_lt_u32_e32 vcc, s41, v47
	s_nop 1
	v_cndmask_b32_e32 v47, v231, v63, vcc
	v_max3_f32 v50, v48, v46, v47
	v_add_u32_e32 v48, 0x57, v2
	v_cmp_lt_u32_e32 vcc, s41, v48
	s_nop 1
	v_cndmask_b32_e32 v48, v231, v64, vcc
	v_cmp_lt_u32_e32 vcc, s41, v49
	s_nop 1
	v_cndmask_b32_e32 v49, v231, v65, vcc
	v_max3_f32 v117, v50, v48, v49
	v_add_u32_e32 v50, 0x59, v2
	v_cmp_lt_u32_e32 vcc, s41, v50
	v_add_u32_e32 v2, 0x5a, v2
	s_nop 0
	v_cndmask_b32_e32 v50, v231, v66, vcc
	v_cmp_lt_u32_e32 vcc, s41, v2
	s_nop 1
	v_cndmask_b32_e32 v51, v231, v67, vcc
	v_max3_f32 v2, v117, v50, v51
	s_cbranch_execnz .LBB0_1712

; #define LAS __attribute__((address_space(3)))
; DI void tile_online(AState& st, const LAS bf16* Kt, int KP, const LAS bf16* Vt, int VP, const bf16x8 (&qf)[4], int kbase, int lo, int hi, bool flag, int r, int h) {
;     const bool any = flag && (kbase + 31 >= lo) && (kbase <= hi);
;     if (__ballot(any) == 0ull) return;
;     f32x16 s = qk_tile32(Kt, KP, qf, r, h);
;     const bool cut = flag && !((kbase >= lo) && (kbase + 31 <= hi));
;     float mx = -__builtin_inff();
;     if (__ballot(cut) != 0ull) {
;         const unsigned t0 = (unsigned)(kbase + 4 * h - lo), range = (unsigned)(hi - lo);
; #pragma unroll
;         for (int reg = 0; reg < 16; ++reg) { s[reg] = (t0 + (unsigned)((reg & 3) + 8 * (reg >> 2)) <= range) ? s[reg] : -__builtin_inff(); mx = fmaxf(mx, s[reg]); }
;     } else {
; #pragma unroll
;         for (int reg = 0; reg < 16; ++reg) mx = fmaxf(mx, s[reg]);
;     }
; DI void nsa_prompt_unit(Frame& F, int b, int kv, int c) {
;     ...
;             if (two) {
;               tile_online(st, KT1, KTP, VT1, VTP, qf, 64 * j + 64, qpos - 511, qpos, true, r, h);
;               tile_online(st, KT1 + 32 * KTP, KTP, VT1 + 32 * VTP, VTP, qf, 64 * j + 96, qpos - 511, qpos, true, r, h);
.LBB0_1715:
	s_add_i32 s2, s6, 0x60
	s_add_i32 s3, s6, 0x7f
	v_cmp_ge_i32_e32 vcc, s3, v114
	v_cmp_le_i32_e64 s[0:1], s2, v104
	s_and_b64 s[0:1], s[0:1], vcc
	s_mov_b64 vcc, s[0:1]
	s_cbranch_vccz .LBB0_1685
	ds_read_b128 v[36:39], v105 offset:23040
	ds_read_b128 v[40:43], v105 offset:23072
	ds_read_b128 v[44:47], v105 offset:23104
	ds_read_b128 v[48:51], v105 offset:23136
	ds_read_b64_tr_b16 v[126:127], v112 offset:32256
	ds_read_b64_tr_b16 v[128:129], v112 offset:33408
	ds_read_b64_tr_b16 v[130:131], v112 offset:32320
	ds_read_b64_tr_b16 v[132:133], v112 offset:33472
	ds_read_b64_tr_b16 v[134:135], v112 offset:34560
	ds_read_b64_tr_b16 v[136:137], v112 offset:35712
	ds_read_b64_tr_b16 v[138:139], v112 offset:34624
	ds_read_b64_tr_b16 v[140:141], v112 offset:35776
	v_cmp_lt_i32_e32 vcc, s2, v114
	v_cmp_gt_i32_e64 s[2:3], s3, v104
	s_or_b64 vcc, vcc, s[2:3]
	s_waitcnt lgkmcnt(11)
	v_mfma_f32_32x32x16_bf16 v[52:67], v[36:39], v[68:71], 0
	s_waitcnt lgkmcnt(10)
	v_mfma_f32_32x32x16_bf16 v[52:67], v[40:43], v[72:75], v[52:67]
	s_waitcnt lgkmcnt(9)
	v_mfma_f32_32x32x16_bf16 v[52:67], v[44:47], v[76:79], v[52:67]
	s_waitcnt lgkmcnt(8)
	v_mfma_f32_32x32x16_bf16 v[52:67], v[48:51], v[80:83], v[52:67]
	s_cbranch_vccz .LBB0_1724
	v_add_u32_e32 v2, s6, v115
	v_add_u32_e32 v36, 0x25f, v2
	v_cmp_gt_u32_e32 vcc, s31, v36
	v_add_u32_e32 v37, 0x60, v2
	v_add_u32_e32 v38, 0x61, v2
	s_nop 5
	v_cndmask_b32_e32 v36, v231, v52, vcc
	v_cmp_lt_u32_e32 vcc, s41, v37
	v_add_u32_e32 v39, 0x62, v2
	v_add_u32_e32 v41, 0x68, v2
	v_cndmask_b32_e32 v37, v231, v53, vcc
	v_cmp_lt_u32_e32 vcc, s41, v38
	v_max3_f32 v40, v36, s40, v37
	v_add_u32_e32 v43, 0x6a, v2
	v_cndmask_b32_e32 v38, v231, v54, vcc
	v_cmp_lt_u32_e32 vcc, s41, v39
	v_add_u32_e32 v45, 0x70, v2
	v_add_u32_e32 v47, 0x72, v2
	v_cndmask_b32_e32 v39, v231, v55, vcc
	v_max3_f32 v42, v40, v38, v39
	v_add_u32_e32 v40, 0x67, v2
	v_cmp_lt_u32_e32 vcc, s41, v40
	v_add_u32_e32 v49, 0x78, v2
	s_nop 0
	v_cndmask_b32_e32 v40, v231, v56, vcc
	v_cmp_lt_u32_e32 vcc, s41, v41
	s_nop 1
	v_cndmask_b32_e32 v41, v231, v57, vcc
	v_max3_f32 v44, v42, v40, v41
	v_add_u32_e32 v42, 0x69, v2
	v_cmp_lt_u32_e32 vcc, s41, v42
	s_nop 1
	v_cndmask_b32_e32 v42, v231, v58, vcc
	v_cmp_lt_u32_e32 vcc, s41, v43
	s_nop 1
	v_cndmask_b32_e32 v43, v231, v59, vcc
	v_max3_f32 v46, v44, v42, v43
	v_add_u32_e32 v44, 0x6f, v2
	v_cmp_lt_u32_e32 vcc, s41, v44
	s_nop 1
	v_cndmask_b32_e32 v44, v231, v60, vcc
	v_cmp_lt_u32_e32 vcc, s41, v45
	s_nop 1
	v_cndmask_b32_e32 v45, v231, v61, vcc
	v_max3_f32 v48, v46, v44, v45
	v_add_u32_e32 v46, 0x71, v2
	v_cmp_lt_u32_e32 vcc, s41, v46
	s_nop 1
	v_cndmask_b32_e32 v46, v231, v62, vcc
	v_cmp_lt_u32_e32 vcc, s41, v47
	s_nop 1
	v_cndmask_b32_e32 v47, v231, v63, vcc
	v_max3_f32 v50, v48, v46, v47
	v_add_u32_e32 v48, 0x77, v2
	v_cmp_lt_u32_e32 vcc, s41, v48
	s_nop 1
	v_cndmask_b32_e32 v48, v231, v64, vcc
	v_cmp_lt_u32_e32 vcc, s41, v49
	s_nop 1
	v_cndmask_b32_e32 v49, v231, v65, vcc
	v_max3_f32 v117, v50, v48, v49
	v_add_u32_e32 v50, 0x79, v2
	v_cmp_lt_u32_e32 vcc, s41, v50
	v_add_u32_e32 v2, 0x7a, v2
	s_nop 0
	v_cndmask_b32_e32 v50, v231, v66, vcc
	v_cmp_lt_u32_e32 vcc, s41, v2
	s_nop 1
	v_cndmask_b32_e32 v51, v231, v67, vcc
	v_max3_f32 v2, v117, v50, v51
	s_cbranch_execnz .LBB0_1719
